# hand P11 + U prefetch one sub-block ahead in both S5 loops (P2 s5_wave<false>, P3 s5_wave<true>)
# speedup vs baseline: 1.0007x; 1.0007x over previous
.LBB0_180:
	s_add_i32 s26, s26, s34
	s_cmpk_gt_i32 s26, 0x7ff
	s_cbranch_scc1 .LBB0_186
	s_and_b32 s3, s26, 63
	v_mov_b32_e32 v83, 0
	v_lshlrev_b32_e32 v0, 3, v80
	v_lshl_or_b32 v0, s3, 9, v0
	v_mov_b32_e32 v1, v83
	v_lshl_add_u64 v[0:1], s[60:61], 0, v[0:1]
	s_mov_b32 s4, 0x6480000
	s_mov_b64 s[0:1], 0x6480000
	v_add_co_u32_e32 v2, vcc, s4, v0
	v_lshrrev_b32_e32 v4, 1, v67
	s_nop 0
	v_addc_co_u32_e32 v3, vcc, 0, v1, vcc
	v_lshl_add_u64 v[0:1], v[0:1], 0, s[0:1]
	global_load_dwordx2 v[2:3], v[2:3], off
	s_lshl_b32 s4, s3, 7
	global_load_dwordx2 v[0:1], v[0:1], off offset:256
	v_and_b32_e32 v82, 16, v4
	s_mov_b64 s[0:1], 0x6400000
	v_lshl_add_u64 v[10:11], s[60:61], 0, v[82:83]
	v_or_b32_e32 v4, s4, v80
	v_or_b32_e32 v6, s4, v81
	v_mov_b32_e32 v5, v83
	v_lshl_add_u64 v[10:11], v[10:11], 0, s[0:1]
	v_lshlrev_b32_e32 v4, 5, v4
	v_lshlrev_b32_e32 v8, 5, v6
	v_mov_b32_e32 v7, v83
	v_lshl_add_u64 v[4:5], v[10:11], 0, v[4:5]
	v_or_b32_e32 v6, 0x400, v8
	v_mov_b32_e32 v9, v83
	v_or_b32_e32 v8, 0xc00, v8
	global_load_dwordx4 v[64:67], v[4:5], off
	global_load_dwordx4 v[68:71], v[4:5], off offset:2048
	v_lshl_add_u64 v[4:5], v[10:11], 0, v[6:7]
	v_lshl_add_u64 v[6:7], v[10:11], 0, v[8:9]
	global_load_dwordx4 v[72:75], v[4:5], off
	global_load_dwordx4 v[76:79], v[6:7], off
	v_mbcnt_hi_u32_b32 v4, -1, v213
	v_and_b32_e32 v6, 64, v4
	v_xor_b32_e32 v5, 32, v4
	v_add_u32_e32 v6, 64, v6
	v_cmp_lt_i32_e64 s[0:1], v5, v6
	s_ashr_i32 s4, s26, 10
	s_lshr_b32 s24, s7, 6
	v_cndmask_b32_e64 v4, v4, v5, s[0:1]
	s_bfe_u32 s7, s26, 0x40006
	v_cmp_gt_u32_e32 vcc, 32, v81
	s_ashr_i32 s5, s4, 31
	v_lshlrev_b32_e32 v81, 2, v4
	s_lshl_b32 s25, s7, 9
	s_lshl_b64 s[20:21], s[4:5], 13
	s_or_b32 s0, s20, s25
	v_or_b32_e32 v16, s0, v80
	s_movk_i32 s0, 0x2800
	s_mul_i32 s20, s21, 0x2800
	v_mov_b32_e32 v106, v83
	v_mov_b32_e32 v107, v83
	s_waitcnt vmcnt(5)
	v_pk_mul_f32 v[6:7], v[2:3], v[2:3] op_sel:[1,0] op_sel_hi:[0,1]
	v_mul_f32_e32 v4, v3, v3
	s_waitcnt vmcnt(4)
	v_pk_mul_f32 v[10:11], v[0:1], v[0:1] op_sel:[1,0] op_sel_hi:[0,1]
	v_mul_f32_e32 v8, v1, v1
	v_pk_add_f32 v[6:7], v[6:7], v[6:7]
	v_pk_add_f32 v[10:11], v[10:11], v[10:11]
	v_pk_fma_f32 v[4:5], v[2:3], v[2:3], v[4:5] op_sel_hi:[1,1,0] neg_lo:[0,0,1] neg_hi:[0,0,1]
	v_pk_fma_f32 v[8:9], v[0:1], v[0:1], v[8:9] op_sel_hi:[1,1,0] neg_lo:[0,0,1] neg_hi:[0,0,1]
	v_pk_mul_f32 v[12:13], v[2:3], v[6:7] op_sel:[1,0] op_sel_hi:[0,1]
	v_pk_mul_f32 v[6:7], v[2:3], v[6:7]
	v_pk_mul_f32 v[14:15], v[0:1], v[10:11] op_sel:[1,0] op_sel_hi:[0,1]
	v_pk_mul_f32 v[10:11], v[0:1], v[10:11]
	v_pk_fma_f32 v[12:13], v[2:3], v[4:5], v[12:13] neg_lo:[0,0,1] neg_hi:[0,0,1]
	v_pk_fma_f32 v[4:5], v[2:3], v[4:5], v[6:7] op_sel:[1,0,0] op_sel_hi:[0,1,1]
	v_pk_fma_f32 v[6:7], v[0:1], v[8:9], v[14:15] neg_lo:[0,0,1] neg_hi:[0,0,1]
	v_pk_fma_f32 v[8:9], v[0:1], v[8:9], v[10:11] op_sel:[1,0,0] op_sel_hi:[0,1,1]
	v_pk_mul_f32 v[14:15], v[0:1], v[8:9]
	v_mul_f32_e32 v9, v0, v6
	v_xor_b32_e32 v86, 0x80000000, v1
	v_mov_b32_e32 v92, v0
	v_pk_fma_f32 v[96:97], v[0:1], v[6:7], v[14:15] op_sel:[1,0,0] op_sel_hi:[0,1,1]
	v_fma_f32 v100, -v1, v8, v9
	v_mov_b32_e32 v93, v0
	v_mov_b32_e32 v87, v1
	v_mov_b32_e32 v102, v1
	v_mad_u64_u32 v[0:1], s[0:1], v16, s0, 0
	s_add_i32 s0, s34, s24
	s_and_b32 s0, s0, 63
	s_lshl_b32 s0, s0, 5
	v_pk_mul_f32 v[10:11], v[2:3], v[4:5]
	v_mul_f32_e32 v5, v2, v12
	v_add_u32_e32 v1, s20, v1
	v_or3_b32 v0, v0, s0, v82
	v_xor_b32_e32 v84, 0x80000000, v3
	v_pk_fma_f32 v[94:95], v[2:3], v[12:13], v[10:11] op_sel:[1,0,0] op_sel_hi:[0,1,1]
	v_fma_f32 v98, -v3, v4, v5
	v_lshl_add_u64 v[0:1], s[60:61], 0, v[0:1]
	s_mov_b64 s[0:1], 0xa602000
	v_mov_b32_e32 v88, v2
	v_mov_b32_e32 v89, v2
	v_mov_b32_e32 v85, v3
	v_mov_b32_e32 v90, v3
	v_mov_b32_e32 v91, v84
	v_xor_b32_e32 v95, 0x80000000, v94
	v_xor_b32_e32 v97, 0x80000000, v96
	v_mov_b32_e32 v99, v98
	v_mov_b32_e32 v101, v100
	v_mov_b32_e32 v103, v86
	v_lshl_add_u64 v[104:105], v[0:1], 0, s[0:1]
	s_mov_b64 s[0:1], 0
	v_mov_b32_e32 v82, v83
	v_lshl_add_u64 v[144:145], v[104:105], 0, s[0:1]
	global_load_dwordx4 v[140:143], v[144:145], off
.LBB0_182:
	s_add_u32 s0, s0, 0x50000
	s_addc_u32 s1, s1, 0
	s_cmp_eq_u32 s0, 0x500000
	s_waitcnt vmcnt(0)
	v_mfma_f32_32x32x16_bf16 v[16:31], v[140:143], v[64:67], 0
	s_nop 11
	v_mov_b32_e32 v109, v16
	v_mfma_f32_32x32x16_bf16 v[32:47], v[140:143], v[68:71], 0
	v_mov_b32_e32 v110, v17
	v_mov_b32_e32 v113, v21
	v_mov_b32_e32 v121, v25
	v_mov_b32_e32 v25, v26
	v_mov_b32_e32 v123, v29
	v_mov_b32_e32 v29, v30
	s_nop 5
	v_mov_b32_e32 v108, v32
	v_mfma_f32_32x32x16_bf16 v[0:15], v[140:143], v[72:75], 0
	v_mov_b32_e32 v111, v33
	v_mov_b32_e32 v17, v32
	v_mov_b32_e32 v32, v18
	v_mov_b32_e32 v33, v34
	v_mov_b32_e32 v18, v35
	v_mov_b32_e32 v34, v20
	v_mov_b32_e32 v35, v36
	v_mfma_f32_32x32x16_bf16 v[48:63], v[140:143], v[76:79], 0
	v_lshl_add_u64 v[144:145], v[104:105], 0, s[0:1]
	global_load_dwordx4 v[140:143], v[144:145], off
	v_mov_b32_e32 v112, v37
	s_nop 2
	v_mov_b32_e32 v115, v0
	v_mov_b32_e32 v116, v1
	v_mov_b32_e32 v37, v20
	v_mov_b32_e32 v20, v22
	v_mov_b32_e32 v21, v38
	v_mov_b32_e32 v22, v39
	s_nop 1
	v_mov_b32_e32 v114, v48
	v_mov_b32_e32 v117, v49
	v_mov_b32_e32 v38, v24
	v_mov_b32_e32 v39, v40
	v_mov_b32_e32 v120, v41
	v_mov_b32_e32 v1, v48
	v_mov_b32_e32 v48, v2
	v_mov_b32_e32 v49, v50
	v_mov_b32_e32 v2, v51
	v_mov_b32_e32 v50, v4
	v_mov_b32_e32 v51, v52
	v_mov_b32_e32 v118, v53
	v_mov_b32_e32 v119, v5
	v_mov_b32_e32 v41, v24
	v_mov_b32_e32 v24, v42
	v_mov_b32_e32 v26, v43
	v_mov_b32_e32 v42, v28
	v_mov_b32_e32 v43, v44
	v_mov_b32_e32 v122, v45
	v_mov_b32_e32 v45, v28
	v_mov_b32_e32 v28, v46
	v_mov_b32_e32 v30, v47
	v_mov_b32_e32 v53, v4
	v_mov_b32_e32 v4, v6
	v_mov_b32_e32 v5, v54
	v_mov_b32_e32 v6, v55
	v_mov_b32_e32 v46, v8
	v_mov_b32_e32 v47, v56
	v_mov_b32_e32 v54, v57
	v_mov_b32_e32 v55, v9
	v_mov_b32_e32 v57, v8
	v_mov_b32_e32 v8, v58
	v_mov_b32_e32 v9, v10
	v_mov_b32_e32 v10, v59
	v_mov_b32_e32 v58, v12
	v_mov_b32_e32 v59, v60
	v_mov_b32_e32 v124, v61
	v_mov_b32_e32 v125, v13
	v_mov_b32_e32 v61, v12
	v_mov_b32_e32 v12, v62
	v_mov_b32_e32 v13, v14
	v_mov_b32_e32 v14, v63
	v_pk_fma_f32 v[62:63], v[84:85], v[108:109], v[110:111]
	v_pk_fma_f32 v[34:35], v[90:91], v[34:35], v[112:113]
	v_pk_fma_f32 v[108:109], v[86:87], v[114:115], v[116:117]
	v_pk_fma_f32 v[38:39], v[90:91], v[38:39], v[120:121]
	v_pk_fma_f32 v[50:51], v[102:103], v[50:51], v[118:119]
	v_pk_fma_f32 v[42:43], v[90:91], v[42:43], v[122:123]
	v_pk_fma_f32 v[46:47], v[102:103], v[46:47], v[54:55]
	v_pk_fma_f32 v[54:55], v[102:103], v[58:59], v[124:125]
	v_pk_fma_f32 v[16:17], v[88:89], v[16:17], v[62:63]
	v_pk_fma_f32 v[0:1], v[92:93], v[0:1], v[108:109]
	v_pk_fma_f32 v[34:35], v[88:89], v[36:37], v[34:35]
	v_pk_fma_f32 v[36:37], v[88:89], v[40:41], v[38:39]
	v_pk_fma_f32 v[38:39], v[88:89], v[44:45], v[42:43]
	v_pk_fma_f32 v[40:41], v[92:93], v[52:53], v[50:51]
	v_pk_fma_f32 v[42:43], v[92:93], v[56:57], v[46:47]
	v_pk_fma_f32 v[44:45], v[92:93], v[60:61], v[54:55]
	v_pk_fma_f32 v[32:33], v[84:85], v[16:17], v[32:33] op_sel:[0,1,0] op_sel_hi:[1,0,1]
	v_pk_fma_f32 v[46:47], v[86:87], v[0:1], v[48:49] op_sel:[0,1,0] op_sel_hi:[1,0,1]
	v_pk_fma_f32 v[20:21], v[84:85], v[34:35], v[20:21]
	v_pk_fma_f32 v[24:25], v[90:91], v[36:37], v[24:25] op_sel:[0,1,0] op_sel_hi:[1,0,1]
	v_pk_fma_f32 v[28:29], v[90:91], v[38:39], v[28:29] op_sel:[0,1,0] op_sel_hi:[1,0,1]
	v_pk_fma_f32 v[4:5], v[86:87], v[40:41], v[4:5]
	v_pk_fma_f32 v[8:9], v[102:103], v[42:43], v[8:9] op_sel:[0,1,0] op_sel_hi:[1,0,1]
	v_pk_fma_f32 v[12:13], v[102:103], v[44:45], v[12:13] op_sel:[0,1,0] op_sel_hi:[1,0,1]
	v_pk_fma_f32 v[16:17], v[88:89], v[16:17], v[32:33]
	v_pk_fma_f32 v[0:1], v[92:93], v[0:1], v[46:47]
	v_pk_fma_f32 v[20:21], v[88:89], v[34:35], v[20:21] op_sel:[0,0,1] op_sel_hi:[1,1,0]
	v_pk_fma_f32 v[24:25], v[88:89], v[36:37], v[24:25]
	v_pk_fma_f32 v[28:29], v[88:89], v[38:39], v[28:29]
	v_pk_fma_f32 v[4:5], v[92:93], v[40:41], v[4:5] op_sel:[0,0,1] op_sel_hi:[1,1,0]
	v_pk_fma_f32 v[8:9], v[92:93], v[42:43], v[8:9]
	v_pk_fma_f32 v[12:13], v[92:93], v[44:45], v[12:13]
	v_pk_fma_f32 v[18:19], v[90:91], v[16:17], v[18:19]
	v_pk_fma_f32 v[2:3], v[102:103], v[0:1], v[2:3]
	v_pk_fma_f32 v[22:23], v[90:91], v[20:21], v[22:23] op_sel:[0,1,0] op_sel_hi:[1,0,1]
	v_pk_fma_f32 v[26:27], v[90:91], v[24:25], v[26:27] op_sel:[0,1,0] op_sel_hi:[1,0,1]
	v_pk_fma_f32 v[30:31], v[90:91], v[28:29], v[30:31] op_sel:[0,1,0] op_sel_hi:[1,0,1]
	v_pk_fma_f32 v[6:7], v[102:103], v[4:5], v[6:7] op_sel:[0,1,0] op_sel_hi:[1,0,1]
	v_pk_fma_f32 v[10:11], v[102:103], v[8:9], v[10:11] op_sel:[0,1,0] op_sel_hi:[1,0,1]
	v_pk_fma_f32 v[14:15], v[102:103], v[12:13], v[14:15] op_sel:[0,1,0] op_sel_hi:[1,0,1]
	v_pk_fma_f32 v[16:17], v[88:89], v[16:17], v[18:19] op_sel:[0,1,0] op_sel_hi:[1,0,1]
	v_pk_fma_f32 v[18:19], v[88:89], v[20:21], v[22:23]
	v_pk_fma_f32 v[20:21], v[88:89], v[24:25], v[26:27]
	v_pk_fma_f32 v[0:1], v[92:93], v[0:1], v[2:3] op_sel:[0,1,0] op_sel_hi:[1,0,1]
	v_pk_fma_f32 v[22:23], v[88:89], v[28:29], v[30:31]
	v_pk_fma_f32 v[2:3], v[92:93], v[4:5], v[6:7]
	v_pk_fma_f32 v[4:5], v[92:93], v[8:9], v[10:11]
	v_pk_fma_f32 v[6:7], v[92:93], v[12:13], v[14:15]
	ds_bpermute_b32 v10, v81, v17
	ds_bpermute_b32 v12, v81, v16
	ds_bpermute_b32 v14, v81, v19
	ds_bpermute_b32 v24, v81, v18
	ds_bpermute_b32 v25, v81, v21
	ds_bpermute_b32 v29, v81, v1
	ds_bpermute_b32 v30, v81, v0
	ds_bpermute_b32 v26, v81, v20
	ds_bpermute_b32 v27, v81, v23
	ds_bpermute_b32 v31, v81, v3
	ds_bpermute_b32 v32, v81, v2
	s_waitcnt lgkmcnt(10)
	v_cndmask_b32_e32 v9, v10, v17, vcc
	s_waitcnt lgkmcnt(9)
	v_cndmask_b32_e32 v8, v12, v16, vcc
	v_cndmask_b32_e32 v11, v17, v10, vcc
	v_cndmask_b32_e32 v10, v16, v12, vcc
	s_waitcnt lgkmcnt(8)
	v_cndmask_b32_e32 v13, v14, v19, vcc
	s_waitcnt lgkmcnt(7)
	v_cndmask_b32_e32 v12, v24, v18, vcc
	v_cndmask_b32_e32 v15, v19, v14, vcc
	v_cndmask_b32_e32 v14, v18, v24, vcc
	s_waitcnt lgkmcnt(6)
	v_cndmask_b32_e32 v17, v25, v21, vcc
	v_cndmask_b32_e32 v19, v21, v25, vcc
	s_waitcnt lgkmcnt(5)
	v_cndmask_b32_e32 v25, v29, v1, vcc
	s_waitcnt lgkmcnt(4)
	v_cndmask_b32_e32 v24, v30, v0, vcc
	v_pk_fma_f32 v[8:9], v[94:95], v[82:83], v[8:9] op_sel:[0,1,0] op_sel_hi:[1,0,1]
	v_pk_fma_f32 v[24:25], v[96:97], v[106:107], v[24:25] op_sel:[0,1,0] op_sel_hi:[1,0,1]
	v_cndmask_b32_e32 v1, v1, v29, vcc
	v_cndmask_b32_e32 v0, v0, v30, vcc
	v_pk_fma_f32 v[8:9], v[98:99], v[82:83], v[8:9]
	v_pk_fma_f32 v[24:25], v[100:101], v[106:107], v[24:25]
	ds_bpermute_b32 v28, v81, v22
	ds_bpermute_b32 v33, v81, v5
	ds_bpermute_b32 v34, v81, v4
	v_pk_fma_f32 v[10:11], v[94:95], v[8:9], v[10:11] op_sel:[0,1,0] op_sel_hi:[1,0,1]
	v_pk_fma_f32 v[0:1], v[96:97], v[24:25], v[0:1] op_sel:[0,1,0] op_sel_hi:[1,0,1]
	s_waitcnt lgkmcnt(6)
	v_cndmask_b32_e32 v16, v26, v20, vcc
	v_cndmask_b32_e32 v18, v20, v26, vcc
	s_waitcnt lgkmcnt(5)
	v_cndmask_b32_e32 v21, v27, v23, vcc
	v_cndmask_b32_e32 v23, v23, v27, vcc
	s_waitcnt lgkmcnt(4)
	v_cndmask_b32_e32 v27, v31, v3, vcc
	s_waitcnt lgkmcnt(3)
	v_cndmask_b32_e32 v26, v32, v2, vcc
	v_pk_fma_f32 v[8:9], v[98:99], v[8:9], v[10:11]
	v_pk_fma_f32 v[0:1], v[100:101], v[24:25], v[0:1]
	v_pk_fma_f32 v[10:11], v[94:95], v[8:9], v[12:13] op_sel:[0,1,0] op_sel_hi:[1,0,1]
	v_pk_fma_f32 v[12:13], v[96:97], v[0:1], v[26:27] op_sel:[0,1,0] op_sel_hi:[1,0,1]
	v_cndmask_b32_e32 v3, v3, v31, vcc
	v_cndmask_b32_e32 v2, v2, v32, vcc
	v_pk_fma_f32 v[8:9], v[98:99], v[8:9], v[10:11]
	v_pk_fma_f32 v[0:1], v[100:101], v[0:1], v[12:13]
	ds_bpermute_b32 v35, v81, v7
	ds_bpermute_b32 v36, v81, v6
	v_pk_fma_f32 v[10:11], v[94:95], v[8:9], v[14:15] op_sel:[0,1,0] op_sel_hi:[1,0,1]
	v_pk_fma_f32 v[2:3], v[96:97], v[0:1], v[2:3] op_sel:[0,1,0] op_sel_hi:[1,0,1]
	s_waitcnt lgkmcnt(4)
	v_cndmask_b32_e32 v20, v28, v22, vcc
	v_cndmask_b32_e32 v22, v22, v28, vcc
	s_waitcnt lgkmcnt(3)
	v_cndmask_b32_e32 v29, v33, v5, vcc
	s_waitcnt lgkmcnt(2)
	v_cndmask_b32_e32 v28, v34, v4, vcc
	v_pk_fma_f32 v[8:9], v[98:99], v[8:9], v[10:11]
	v_pk_fma_f32 v[0:1], v[100:101], v[0:1], v[2:3]
	v_pk_fma_f32 v[2:3], v[94:95], v[8:9], v[16:17] op_sel:[0,1,0] op_sel_hi:[1,0,1]
	v_pk_fma_f32 v[10:11], v[96:97], v[0:1], v[28:29] op_sel:[0,1,0] op_sel_hi:[1,0,1]
	v_cndmask_b32_e32 v5, v5, v33, vcc
	v_cndmask_b32_e32 v4, v4, v34, vcc
	v_pk_fma_f32 v[2:3], v[98:99], v[8:9], v[2:3]
	v_pk_fma_f32 v[0:1], v[100:101], v[0:1], v[10:11]
	v_pk_fma_f32 v[8:9], v[94:95], v[2:3], v[18:19] op_sel:[0,1,0] op_sel_hi:[1,0,1]
	v_pk_fma_f32 v[4:5], v[96:97], v[0:1], v[4:5] op_sel:[0,1,0] op_sel_hi:[1,0,1]
	s_waitcnt lgkmcnt(1)
	v_cndmask_b32_e32 v31, v35, v7, vcc
	s_waitcnt lgkmcnt(0)
	v_cndmask_b32_e32 v30, v36, v6, vcc
	v_pk_fma_f32 v[2:3], v[98:99], v[2:3], v[8:9]
	v_pk_fma_f32 v[0:1], v[100:101], v[0:1], v[4:5]
	v_pk_fma_f32 v[4:5], v[94:95], v[2:3], v[20:21] op_sel:[0,1,0] op_sel_hi:[1,0,1]
	v_pk_fma_f32 v[8:9], v[96:97], v[0:1], v[30:31] op_sel:[0,1,0] op_sel_hi:[1,0,1]
	v_cndmask_b32_e32 v7, v7, v35, vcc
	v_cndmask_b32_e32 v6, v6, v36, vcc
	v_pk_fma_f32 v[2:3], v[98:99], v[2:3], v[4:5]
	v_pk_fma_f32 v[0:1], v[100:101], v[0:1], v[8:9]
	v_pk_fma_f32 v[4:5], v[94:95], v[2:3], v[22:23] op_sel:[0,1,0] op_sel_hi:[1,0,1]
	v_pk_fma_f32 v[6:7], v[96:97], v[0:1], v[6:7] op_sel:[0,1,0] op_sel_hi:[1,0,1]
	v_pk_fma_f32 v[82:83], v[98:99], v[2:3], v[4:5]
	v_pk_fma_f32 v[106:107], v[100:101], v[0:1], v[6:7]
	s_cbranch_scc0 .LBB0_182
	s_and_saveexec_b64 s[0:1], vcc
	s_cbranch_execz .LBB0_185
	s_lshl_b32 s7, s7, 6
	s_lshl_b64 s[4:5], s[4:5], 10
	s_or_b32 s4, s4, s7
	s_or_b32 s4, s4, s3
	s_lshl_b64 s[4:5], s[4:5], 9
	s_add_u32 s4, s60, s4
	s_addc_u32 s5, s61, s5
	v_lshlrev_b32_e32 v2, 3, v80
	v_mov_b32_e32 v3, 0
	v_lshl_add_u64 v[2:3], s[4:5], 0, v[2:3]
	s_mov_b64 s[4:5], 0x6500000
	v_lshl_add_u64 v[4:5], v[2:3], 0, s[4:5]
	v_add_co_u32_e32 v2, vcc, 0x6500000, v2
	v_pk_mov_b32 v[0:1], v[82:83], v[82:83] op_sel:[1,0]
	s_nop 0
	v_addc_co_u32_e32 v3, vcc, 0, v3, vcc
	global_store_dwordx2 v[2:3], v[0:1], off
	v_pk_mov_b32 v[0:1], v[106:107], v[106:107] op_sel:[1,0]
	global_store_dwordx2 v[4:5], v[0:1], off offset:256
